# P5 entry: xb decode-row copy stores deferred behind the GEMM prologue's first counted wait (no exposed wait)
# baseline (speedup 1.0000x reference)
.Lt5_entry:
	s_cmp_lg_u32 s97, 0
	s_cbranch_scc1 .Lt5_nocp
	s_lshl_b32 s4, s2, 9
	v_add_lshl_u32 v240, s4, v176, 5
	s_add_u32 s4, s30, 0x10a00000
	s_addc_u32 s5, s31, 0
	global_load_dwordx4 v[242:245], v240, s[4:5]
	global_load_dwordx4 v[246:249], v240, s[4:5] offset:16

.LBB0_939:
	v_bfe_u32 v16, v14, 4, 2
	v_and_b32_e32 v15, 15, v14
	v_lshlrev_b32_e32 v17, 4, v16
	v_lshlrev_b32_e32 v14, 2, v14
	s_sext_i32_i16 s43, s4
	v_lshl_or_b32 v152, s6, 6, v15
	v_lshl_or_b32 v15, v15, 6, v17
	s_lshl_b32 s4, s6, 13
	v_and_b32_e32 v14, 32, v14
	v_bitop3_b32 v17, v15, s4, v14 bitop3:0xde
	s_lshl_b32 s4, s5, 5
	s_mov_b64 s[6:7], 0x80
	s_and_b32 s10, s4, 0x60
	s_add_i32 m0, s17, 0x18000
	v_lshl_add_u64 v[6:7], v[6:7], 0, s[6:7]
	s_lshl_b32 s4, s10, 7
	s_waitcnt vmcnt(4)
	s_cmp_lg_u32 s97, 0
	s_cbranch_scc1 .Lt5_nost
	s_add_u32 s98, s30, 0xc600000
	s_addc_u32 s99, s31, 0
	global_store_dwordx4 v240, v[242:245], s[98:99]
	global_store_dwordx4 v240, v[246:249], s[98:99] offset:16
.Lt5_nost:
	s_barrier
	global_load_lds_dwordx4 v[6:7], off
	v_lshl_add_u64 v[4:5], v[4:5], 0, s[6:7]
	s_add_i32 m0, s17, 0x1a000
	s_add_i32 s37, s17, 0x8000
	s_add_i32 s38, s17, 0xa000
	v_bitop3_b32 v153, v15, s4, v14 bitop3:0xde
	global_load_lds_dwordx4 v[4:5], off
	v_lshl_add_u64 v[2:3], v[2:3], 0, s[6:7]
	s_mov_b32 m0, s37
	s_add_u32 s4, s20, 0x80080
	global_load_lds_dwordx4 v[2:3], off
	v_lshl_add_u64 v[0:1], v[0:1], 0, s[6:7]
	s_mov_b32 m0, s38
	s_addc_u32 s5, s21, 0
	global_load_lds_dwordx4 v[0:1], off
	s_add_i32 m0, s17, 0x1c000
	v_lshl_add_u64 v[0:1], s[4:5], 0, v[132:133]
	global_load_lds_dwordx4 v[0:1], off
	v_lshl_add_u64 v[0:1], s[4:5], 0, v[128:129]
	s_add_i32 m0, s17, 0x1e000
	s_add_i32 s39, 0, 0x10000
	global_load_lds_dwordx4 v[0:1], off
	v_lshlrev_b32_e32 v0, 5, v16
	v_mov_b32_e32 v1, v133
	v_lshl_add_u64 v[136:137], s[8:9], 0, v[0:1]
	v_lshlrev_b32_e32 v0, 15, v12
	v_and_b32_e32 v0, 0xffff0000, v0
	v_lshl_add_u32 v0, v11, 12, v0
	v_and_b32_e32 v1, 1, v12
	v_lshl_or_b32 v0, v1, 6, v0
	v_lshl_add_u32 v138, v13, 1, v0
	v_lshlrev_b32_e32 v0, 15, v8
	v_and_b32_e32 v0, 0xffff0000, v0
	v_lshl_add_u32 v0, v9, 12, v0
	v_and_b32_e32 v1, 1, v8
	s_waitcnt vmcnt(6)
	v_lshl_or_b32 v0, v1, 6, v0
	v_lshl_add_u32 v140, v10, 1, v0
	s_add_i32 s40, 0, 0x14000
	v_mbcnt_lo_u32_b32 v0, -1, 0
	v_lshl_or_b32 v154, v16, 3, s10
	v_mov_b32_e32 v139, v133
	v_mov_b32_e32 v141, v133
	v_mov_b64_e32 v[142:143], 0x600
	v_mov_b64_e32 v[144:145], 0x5ff
	v_add_u32_e32 v155, s39, v153
	v_add_u32_e32 v156, 0, v17
	v_add_u32_e32 v157, s40, v153
	v_mbcnt_hi_u32_b32 v158, -1, v0
	v_mov_b32_e32 v159, 0x358637bd
	s_mov_b32 s41, 0x800000
	s_movk_i32 s42, 0x5800
	s_barrier
